# G1B to GMA grid barrier replaced by a workgroup-level drain+barrier (each workgroup consumes only the gate tiles it produced; regions disjoint)
# speedup vs baseline: 1.0117x; 1.0046x over previous
.Lg1b_fin:
	s_waitcnt vmcnt(0) lgkmcnt(0)
	s_barrier
	s_branch .LBB0_1163
	s_load_dword s0, s[88:89], 0xdc
	s_waitcnt lgkmcnt(0)
	s_cmp_lt_i32 s0, 11
	s_cbranch_scc1 .LBB0_1163
	s_getreg_b32 s0, hwreg(HW_REG_XCC_ID, 0, 4)
	s_cmp_lg_u32 s92, 0
	s_mov_b64 s[4:5], 0
	s_cbranch_scc1 .LBB0_1110
	v_mbcnt_lo_u32_b32 v0, -1, 0
	v_mbcnt_hi_u32_b32 v0, -1, v0
	s_nop 0
	v_cmp_eq_u32_e32 vcc, 0, v0
	s_and_b64 s[4:5], vcc, exec
